# in-proj: per-tile bias loads issued under the last 10 MFMAs of the K tail (clamped index, masked in the epilogue) instead of after them
# baseline (speedup 1.0000x reference)
; DEV f32x16 mfma32(bf16x8 a, bf16x8 b, f32x16 c) { return __builtin_amdgcn_mfma_f32_32x32x16_bf16(a, b, c, 0, 0, 0); }
; template <int EPI>
; __device__ void gemm_phase256(const Params& P, int l, const bf16_t* __restrict__ A, const bf16_t* __restrict__ Bt, int NT, char* smem) {
;     ...
;     for (int kt = 0; kt < 16; ++kt) {
;       __syncthreads();
;       {
;         bf16_t* as = As + lrow * 72 + lc8; bf16_t* bs = Bs + lrow * 72 + lc8;
;         *(uint4*)(as) = ra0; *(uint4*)(as + 32 * 72) = ra1; *(uint4*)(as + 64 * 72) = ra2; *(uint4*)(as + 96 * 72) = ra3;
;         *(uint4*)(as + 128 * 72) = ra4; *(uint4*)(as + 160 * 72) = ra5; *(uint4*)(as + 192 * 72) = ra6; *(uint4*)(as + 224 * 72) = ra7;
;         *(uint4*)(bs) = rb0; *(uint4*)(bs + 32 * 72) = rb1; *(uint4*)(bs + 64 * 72) = rb2; *(uint4*)(bs + 96 * 72) = rb3;
;       }
;       __syncthreads();
;       {
;         const int k0 = (kt + 1 < 16) ? (kt + 1) * 64 : 15 * 64;
;         GLOAD2(k0);
;       }
; #pragma unroll
;       for (int kk = 0; kk < 4; ++kk) {
;         bf16x8 af[4], bfr[2];
; #pragma unroll
;         for (int mi = 0; mi < 4; ++mi) af[mi] = *(const bf16x8*)(As + (wm * 128 + mi * 32 + lr) * 72 + kk * 16 + hk * 8);
; #pragma unroll
;         for (int ni = 0; ni < 2; ++ni) bfr[ni] = *(const bf16x8*)(Bs + (wn * 64 + ni * 32 + lr) * 72 + kk * 16 + hk * 8);
; #pragma unroll
;         for (int mi = 0; mi < 4; ++mi)
; #pragma unroll
;           for (int ni = 0; ni < 2; ++ni) acc[mi][ni] = mfma32(af[mi], bfr[ni], acc[mi][ni]);
;       }
;     }
.LBB0_240:
	s_barrier
	s_waitcnt vmcnt(10)
	ds_write_b128 v184, v[128:131]
	s_waitcnt vmcnt(9)
	ds_write_b128 v184, v[136:139] offset:4608
	s_waitcnt vmcnt(8)
	ds_write_b128 v184, v[140:143] offset:9216
	s_waitcnt vmcnt(7)
	ds_write_b128 v184, v[144:147] offset:13824
	s_waitcnt vmcnt(6)
	ds_write_b128 v184, v[148:151] offset:18432
	s_waitcnt vmcnt(5)
	ds_write_b128 v184, v[152:155] offset:23040
	s_waitcnt vmcnt(4)
	ds_write_b128 v184, v[156:159] offset:27648
	s_waitcnt vmcnt(3)
	ds_write_b128 v184, v[160:163] offset:32256
	s_waitcnt vmcnt(3)
	ds_write_b128 v184, v[132:135] offset:36864
	s_waitcnt vmcnt(2)
	ds_write_b128 v184, v[164:167] offset:41472
	s_waitcnt vmcnt(1)
	ds_write_b128 v184, v[168:171] offset:46080
	s_waitcnt vmcnt(0)
	ds_write_b128 v184, v[172:175] offset:50688
	s_waitcnt lgkmcnt(0)
	s_barrier
	ds_read_b128 v[128:131], v231
	ds_read_b128 v[132:135], v233 offset:36864
	ds_read_b128 v[136:139], v231 offset:32
	ds_read_b128 v[140:143], v233 offset:36896
	ds_read_b128 v[144:147], v233 offset:41472
	ds_read_b128 v[148:151], v233 offset:41504
	s_waitcnt lgkmcnt(4)
	v_mfma_f32_32x32x16_bf16 v[112:127], v[128:131], v[132:135], v[112:127]
	s_waitcnt lgkmcnt(1)
	v_mfma_f32_32x32x16_bf16 v[96:111], v[128:131], v[144:147], v[96:111]
	ds_read_b128 v[128:131], v231 offset:4608
	ds_read_b128 v[152:155], v231 offset:4640
	s_waitcnt lgkmcnt(1)
	v_mfma_f32_32x32x16_bf16 v[80:95], v[128:131], v[132:135], v[80:95]
	v_mfma_f32_32x32x16_bf16 v[64:79], v[128:131], v[144:147], v[64:79]
	ds_read_b128 v[128:131], v231 offset:9216
	ds_read_b128 v[156:159], v231 offset:9248
	s_waitcnt lgkmcnt(1)
	v_mfma_f32_32x32x16_bf16 v[48:63], v[128:131], v[132:135], v[48:63]
	v_mfma_f32_32x32x16_bf16 v[32:47], v[128:131], v[144:147], v[32:47]
	ds_read_b128 v[128:131], v232
	ds_read_b128 v[160:163], v232 offset:32
	s_waitcnt lgkmcnt(1)
	v_mfma_f32_32x32x16_bf16 v[16:31], v[128:131], v[132:135], v[16:31]
	v_mfma_f32_32x32x16_bf16 v[112:127], v[136:139], v[140:143], v[112:127]
	v_mfma_f32_32x32x16_bf16 v[96:111], v[136:139], v[148:151], v[96:111]
	v_mfma_f32_32x32x16_bf16 v[0:15], v[128:131], v[144:147], v[0:15]
	ds_read_b128 v[128:131], v231 offset:64
	ds_read_b128 v[132:135], v233 offset:36928
	ds_read_b128 v[136:139], v231 offset:96
	ds_read_b128 v[172:175], v233 offset:36960
	v_mfma_f32_32x32x16_bf16 v[80:95], v[152:155], v[140:143], v[80:95]
	v_mfma_f32_32x32x16_bf16 v[64:79], v[152:155], v[148:151], v[64:79]
	v_lshl_add_u64 v[152:153], v[198:199], 0, s[38:39]
	v_mfma_f32_32x32x16_bf16 v[48:63], v[156:159], v[140:143], v[48:63]
	s_waitcnt lgkmcnt(4)
	v_mfma_f32_32x32x16_bf16 v[16:31], v[160:163], v[140:143], v[16:31]
	ds_read_b128 v[140:143], v233 offset:41536
	ds_read_b128 v[238:241], v233 offset:41568
	v_mfma_f32_32x32x16_bf16 v[32:47], v[156:159], v[148:151], v[32:47]
	s_waitcnt lgkmcnt(4)
	v_mfma_f32_32x32x16_bf16 v[112:127], v[128:131], v[132:135], v[112:127]
	s_waitcnt lgkmcnt(1)
	v_mfma_f32_32x32x16_bf16 v[96:111], v[128:131], v[140:143], v[96:111]
	ds_read_b128 v[128:131], v231 offset:4672
	ds_read_b128 v[144:147], v231 offset:4704
	v_mfma_f32_32x32x16_bf16 v[0:15], v[160:163], v[148:151], v[0:15]
	s_waitcnt lgkmcnt(1)
	v_mfma_f32_32x32x16_bf16 v[80:95], v[128:131], v[132:135], v[80:95]
	v_mfma_f32_32x32x16_bf16 v[64:79], v[128:131], v[140:143], v[64:79]
	ds_read_b128 v[128:131], v231 offset:9280
	ds_read_b128 v[148:151], v231 offset:9312
	s_waitcnt lgkmcnt(1)
	v_mfma_f32_32x32x16_bf16 v[48:63], v[128:131], v[132:135], v[48:63]
	v_mfma_f32_32x32x16_bf16 v[32:47], v[128:131], v[140:143], v[32:47]
	ds_read_b128 v[128:131], v232 offset:64
	ds_read_b128 v[242:245], v232 offset:96
	s_waitcnt lgkmcnt(1)
	v_mfma_f32_32x32x16_bf16 v[0:15], v[128:131], v[140:143], v[0:15]
	v_add_co_u32_e32 v140, vcc, s37, v152
	s_nop 1
	v_addc_co_u32_e32 v141, vcc, 0, v153, vcc
	v_add_co_u32_e32 v142, vcc, s40, v152
	v_mfma_f32_32x32x16_bf16 v[16:31], v[128:131], v[132:135], v[16:31]
	s_nop 0
	v_addc_co_u32_e32 v143, vcc, 0, v153, vcc
	v_add_co_u32_e32 v154, vcc, s41, v152
	v_lshl_add_u64 v[128:129], v[200:201], 0, s[38:39]
	s_nop 0
	v_addc_co_u32_e32 v155, vcc, 0, v153, vcc
	v_add_co_u32_e32 v156, vcc, s42, v152
	v_mfma_f32_32x32x16_bf16 v[112:127], v[136:139], v[172:175], v[112:127]
	s_nop 0
	v_addc_co_u32_e32 v157, vcc, 0, v153, vcc
	v_add_co_u32_e32 v158, vcc, s43, v152
	global_load_dwordx4 v[132:135], v[128:129], off offset:128
	s_nop 0
	v_addc_co_u32_e32 v159, vcc, 0, v153, vcc
	v_add_co_u32_e32 v160, vcc, s44, v152
	v_mfma_f32_32x32x16_bf16 v[96:111], v[136:139], v[238:241], v[96:111]
	s_nop 0
	v_addc_co_u32_e32 v161, vcc, 0, v153, vcc
	v_add_co_u32_e32 v162, vcc, s1, v152
	s_add_u32 s38, s38, 0x80
	s_nop 0
	v_addc_co_u32_e32 v163, vcc, 0, v153, vcc
	v_add_co_u32_e32 v164, vcc, s37, v128
	v_mfma_f32_32x32x16_bf16 v[80:95], v[144:147], v[172:175], v[80:95]
	s_nop 0
	v_addc_co_u32_e32 v165, vcc, 0, v129, vcc
	v_add_co_u32_e32 v168, vcc, s40, v128
	s_addc_u32 s39, s39, 0
	s_nop 0
	v_addc_co_u32_e32 v169, vcc, 0, v129, vcc
	v_add_co_u32_e32 v246, vcc, s41, v128
	v_mfma_f32_32x32x16_bf16 v[64:79], v[144:147], v[238:241], v[64:79]
	s_nop 0
	v_addc_co_u32_e32 v247, vcc, 0, v129, vcc
	global_load_dwordx4 v[128:131], v[152:153], off offset:128
	global_load_dwordx4 v[136:139], v[140:141], off offset:128
	s_nop 0
	global_load_dwordx4 v[140:143], v[142:143], off offset:128
	s_cmpk_eq_i32 s38, 0x780
	v_mfma_f32_32x32x16_bf16 v[48:63], v[148:151], v[172:175], v[48:63]
	v_mfma_f32_32x32x16_bf16 v[32:47], v[148:151], v[238:241], v[32:47]
	global_load_dwordx4 v[144:147], v[154:155], off offset:128
	global_load_dwordx4 v[148:151], v[156:157], off offset:128
	s_nop 0
	global_load_dwordx4 v[152:155], v[158:159], off offset:128
	s_nop 0
	global_load_dwordx4 v[156:159], v[160:161], off offset:128
	s_nop 0
	global_load_dwordx4 v[160:163], v[162:163], off offset:128
	s_nop 0
	global_load_dwordx4 v[164:167], v[164:165], off offset:128
	s_nop 0
	global_load_dwordx4 v[168:171], v[168:169], off offset:128
	s_waitcnt lgkmcnt(0)
	v_mfma_f32_32x32x16_bf16 v[16:31], v[242:245], v[172:175], v[16:31]
	global_load_dwordx4 v[172:175], v[246:247], off offset:128
	v_mfma_f32_32x32x16_bf16 v[0:15], v[242:245], v[238:241], v[0:15]
	s_cbranch_scc0 .LBB0_240
; DEV f32x16 mfma32(bf16x8 a, bf16x8 b, f32x16 c) { return __builtin_amdgcn_mfma_f32_32x32x16_bf16(a, b, c, 0, 0, 0); }
; template <int EPI>
; __device__ void gemm_phase256(const Params& P, int l, const bf16_t* __restrict__ A, const bf16_t* __restrict__ Bt, int NT, char* smem) {
;     ...
;     for (int kt = 0; kt < 16; ++kt) {
;       __syncthreads();
;       {
;         bf16_t* as = As + lrow * 72 + lc8; bf16_t* bs = Bs + lrow * 72 + lc8;
;         *(uint4*)(as) = ra0; *(uint4*)(as + 32 * 72) = ra1; *(uint4*)(as + 64 * 72) = ra2; *(uint4*)(as + 96 * 72) = ra3;
;         *(uint4*)(as + 128 * 72) = ra4; *(uint4*)(as + 160 * 72) = ra5; *(uint4*)(as + 192 * 72) = ra6; *(uint4*)(as + 224 * 72) = ra7;
;         *(uint4*)(bs) = rb0; *(uint4*)(bs + 32 * 72) = rb1; *(uint4*)(bs + 64 * 72) = rb2; *(uint4*)(bs + 96 * 72) = rb3;
;       }
;       __syncthreads();
;       {
;         const int k0 = (kt + 1 < 16) ? (kt + 1) * 64 : 15 * 64;
;         GLOAD2(k0);
;       }
; #pragma unroll
;       for (int kk = 0; kk < 4; ++kk) {
;         bf16x8 af[4], bfr[2];
; #pragma unroll
;         for (int mi = 0; mi < 4; ++mi) af[mi] = *(const bf16x8*)(As + (wm * 128 + mi * 32 + lr) * 72 + kk * 16 + hk * 8);
; #pragma unroll
;         for (int ni = 0; ni < 2; ++ni) bfr[ni] = *(const bf16x8*)(Bs + (wn * 64 + ni * 32 + lr) * 72 + kk * 16 + hk * 8);
; #pragma unroll
;         for (int mi = 0; mi < 4; ++mi)
; #pragma unroll
;           for (int ni = 0; ni < 2; ++ni) acc[mi][ni] = mfma32(af[mi], bfr[ni], acc[mi][ni]);
;       }
;     }
;     ...
;           const float bias = (EPI == 0) ? ((n < NIN) ? P.b_in[l * NIN + n] : 0.f) : 0.f;
	s_barrier
	s_waitcnt vmcnt(10)
	ds_write_b128 v184, v[128:131]
	s_waitcnt vmcnt(9)
	ds_write_b128 v184, v[136:139] offset:4608
	s_waitcnt vmcnt(8)
	ds_write_b128 v184, v[140:143] offset:9216
	s_waitcnt vmcnt(7)
	ds_write_b128 v184, v[144:147] offset:13824
	s_waitcnt vmcnt(6)
	ds_write_b128 v184, v[148:151] offset:18432
	s_waitcnt vmcnt(5)
	ds_write_b128 v184, v[152:155] offset:23040
	s_waitcnt vmcnt(4)
	ds_write_b128 v184, v[156:159] offset:27648
	s_waitcnt vmcnt(3)
	ds_write_b128 v184, v[160:163] offset:32256
	ds_write_b128 v184, v[132:135] offset:36864
	s_waitcnt vmcnt(2)
	ds_write_b128 v184, v[164:167] offset:41472
	s_waitcnt vmcnt(1)
	ds_write_b128 v184, v[168:171] offset:46080
	s_waitcnt vmcnt(0)
	ds_write_b128 v184, v[172:175] offset:50688
	s_waitcnt lgkmcnt(0)
	s_barrier
	ds_read_b128 v[128:131], v231
	ds_read_b128 v[132:135], v233 offset:36864
	ds_read_b128 v[136:139], v231 offset:32
	ds_read_b128 v[140:143], v233 offset:36896
	ds_read_b128 v[144:147], v233 offset:41472
	ds_read_b128 v[148:151], v233 offset:41504
	s_waitcnt lgkmcnt(4)
	v_mfma_f32_32x32x16_bf16 v[112:127], v[128:131], v[132:135], v[112:127]
	s_cmp_lt_i32 s33, 17
	s_waitcnt lgkmcnt(1)
	v_mfma_f32_32x32x16_bf16 v[96:111], v[128:131], v[144:147], v[96:111]
	ds_read_b128 v[128:131], v231 offset:4608
	ds_read_b128 v[152:155], v231 offset:4640
	s_waitcnt lgkmcnt(1)
	v_mfma_f32_32x32x16_bf16 v[80:95], v[128:131], v[132:135], v[80:95]
	v_mfma_f32_32x32x16_bf16 v[64:79], v[128:131], v[144:147], v[64:79]
	ds_read_b128 v[128:131], v231 offset:9216
	ds_read_b128 v[156:159], v231 offset:9248
	s_waitcnt lgkmcnt(1)
	v_mfma_f32_32x32x16_bf16 v[48:63], v[128:131], v[132:135], v[48:63]
	v_mfma_f32_32x32x16_bf16 v[32:47], v[128:131], v[144:147], v[32:47]
	ds_read_b128 v[128:131], v232
	ds_read_b128 v[160:163], v232 offset:32
	s_waitcnt lgkmcnt(1)
	v_mfma_f32_32x32x16_bf16 v[16:31], v[128:131], v[132:135], v[16:31]
	v_mfma_f32_32x32x16_bf16 v[0:15], v[128:131], v[144:147], v[0:15]
	v_mfma_f32_32x32x16_bf16 v[112:127], v[136:139], v[140:143], v[112:127]
	v_mfma_f32_32x32x16_bf16 v[96:111], v[136:139], v[148:151], v[96:111]
	v_mfma_f32_32x32x16_bf16 v[80:95], v[152:155], v[140:143], v[80:95]
	v_mfma_f32_32x32x16_bf16 v[64:79], v[152:155], v[148:151], v[64:79]
	v_mfma_f32_32x32x16_bf16 v[48:63], v[156:159], v[140:143], v[48:63]
	v_mfma_f32_32x32x16_bf16 v[32:47], v[156:159], v[148:151], v[32:47]
	s_waitcnt lgkmcnt(0)
	v_mfma_f32_32x32x16_bf16 v[16:31], v[160:163], v[140:143], v[16:31]
	ds_read_b128 v[128:131], v231 offset:64
	ds_read_b128 v[132:135], v233 offset:36928
	ds_read_b128 v[136:139], v231 offset:96
	ds_read_b128 v[140:143], v233 offset:36960
	v_mfma_f32_32x32x16_bf16 v[0:15], v[160:163], v[148:151], v[0:15]
	ds_read_b128 v[144:147], v233 offset:41536
	ds_read_b128 v[148:151], v233 offset:41568
	s_waitcnt lgkmcnt(4)
	v_mfma_f32_32x32x16_bf16 v[112:127], v[128:131], v[132:135], v[112:127]
	s_waitcnt lgkmcnt(1)
	v_mfma_f32_32x32x16_bf16 v[96:111], v[128:131], v[144:147], v[96:111]
	ds_read_b128 v[128:131], v231 offset:4672
	ds_read_b128 v[152:155], v231 offset:4704
	s_waitcnt lgkmcnt(1)
	v_mfma_f32_32x32x16_bf16 v[80:95], v[128:131], v[132:135], v[80:95]
	v_mfma_f32_32x32x16_bf16 v[64:79], v[128:131], v[144:147], v[64:79]
	ds_read_b128 v[128:131], v231 offset:9280
	ds_read_b128 v[156:159], v231 offset:9312
	s_waitcnt lgkmcnt(1)
	v_mfma_f32_32x32x16_bf16 v[48:63], v[128:131], v[132:135], v[48:63]
	v_mfma_f32_32x32x16_bf16 v[32:47], v[128:131], v[144:147], v[32:47]
	ds_read_b128 v[128:131], v232 offset:64
	ds_read_b128 v[160:163], v232 offset:96
	s_waitcnt lgkmcnt(0)
	s_barrier
	v_readlane_b32 s38, v248, 21
	v_readlane_b32 s44, v251, 14
	v_readlane_b32 s45, v251, 15
	v_or_b32_e32 v166, s0, v186
	v_or_b32_e32 v168, s0, v227
	v_mfma_f32_32x32x16_bf16 v[16:31], v[128:131], v[132:135], v[16:31]
	v_min_i32_e32 v166, 0x917, v166
	v_min_i32_e32 v168, 0x917, v168
	v_mfma_f32_32x32x16_bf16 v[0:15], v[128:131], v[144:147], v[0:15]
	v_add_u32_e32 v166, s38, v166
	v_add_u32_e32 v168, s38, v168
	v_mfma_f32_32x32x16_bf16 v[112:127], v[136:139], v[140:143], v[112:127]
	v_ashrrev_i32_e32 v167, 31, v166
	v_ashrrev_i32_e32 v169, 31, v168
	v_mfma_f32_32x32x16_bf16 v[96:111], v[136:139], v[148:151], v[96:111]
	v_lshl_add_u64 v[166:167], v[166:167], 2, s[44:45]
	v_lshl_add_u64 v[168:169], v[168:169], 2, s[44:45]
	v_mfma_f32_32x32x16_bf16 v[80:95], v[152:155], v[140:143], v[80:95]
	global_load_dword v164, v[166:167], off
	global_load_dword v165, v[168:169], off
	v_mfma_f32_32x32x16_bf16 v[64:79], v[152:155], v[148:151], v[64:79]
	v_mfma_f32_32x32x16_bf16 v[48:63], v[156:159], v[140:143], v[48:63]
	v_mfma_f32_32x32x16_bf16 v[32:47], v[156:159], v[148:151], v[32:47]
	v_mfma_f32_32x32x16_bf16 v[16:31], v[160:163], v[140:143], v[16:31]
	v_mfma_f32_32x32x16_bf16 v[0:15], v[160:163], v[148:151], v[0:15]
	s_cbranch_scc1 .LBB0_243
	s_cmp_lg_u32 s33, 17
	s_mov_b64 s[38:39], -1
	s_cselect_b64 s[40:41], -1, 0
	s_cbranch_execz .LBB0_244
	s_branch .LBB0_245

; DEV unsigned short f2bf(float f) { return (unsigned short)(pack2(f, 0.f) & 0xFFFFu); }
; template <int EPI>
; __device__ void gemm_phase256(const Params& P, int l, const bf16_t* __restrict__ A, const bf16_t* __restrict__ Bt, int NT, char* smem) {
;     ...
; #pragma unroll
;       for (int mi = 0; mi < 4; ++mi)
; #pragma unroll
;         for (int ni = 0; ni < 2; ++ni) {
;           const int col = wn * 64 + ni * 32 + lr;
;           const int n = n0 + col;
;           const float bias = (EPI == 0) ? ((n < NIN) ? P.b_in[l * NIN + n] : 0.f) : 0.f;
;           const int rb = wm * 128 + mi * 32 + 4 * hk;
; #pragma unroll
;           for (int i = 0; i < 16; ++i) Cs[(rb + (i & 3) + 8 * (i >> 2)) * 136 + col] = f2bf(acc[mi][ni][i] + bias);
;         }
.LBB0_247:
	v_or_b32_e32 v128, s0, v186
	s_movk_i32 s1, 0x918
	v_or_b32_e32 v129, s0, v227
	v_cmp_gt_i32_e32 vcc, s1, v128
	v_cmp_gt_i32_e64 s[40:41], s1, v129
	s_waitcnt vmcnt(0)
	v_cndmask_b32_e32 v129, 0, v164, vcc
	v_cndmask_b32_e64 v130, 0, v165, s[40:41]
	v_mov_b32_e32 v140, v129
	v_mov_b32_e32 v141, v130
	v_add_f32_e32 v131, v112, v129
	v_cvt_pk_bf16_f32 v131, v131, s0
	ds_write_b16 v228, v131
	v_add_f32_e32 v131, v113, v129
	v_cvt_pk_bf16_f32 v131, v131, s0
	ds_write_b16 v228, v131 offset:272
	v_add_f32_e32 v131, v114, v129
	v_cvt_pk_bf16_f32 v131, v131, s0
	ds_write_b16 v228, v131 offset:544
	v_add_f32_e32 v131, v115, v129
	v_cvt_pk_bf16_f32 v131, v131, s0
	ds_write_b16 v228, v131 offset:816
	v_add_f32_e32 v131, v116, v129
	v_cvt_pk_bf16_f32 v131, v131, s0
	ds_write_b16 v228, v131 offset:2176
	v_add_f32_e32 v131, v117, v129
	v_cvt_pk_bf16_f32 v131, v131, s0
	ds_write_b16 v228, v131 offset:2448
	v_add_f32_e32 v131, v118, v129
	v_cvt_pk_bf16_f32 v131, v131, s0
	ds_write_b16 v228, v131 offset:2720
	v_add_f32_e32 v131, v119, v129
	v_cvt_pk_bf16_f32 v131, v131, s0
	ds_write_b16 v228, v131 offset:2992
	v_add_f32_e32 v131, v120, v129
	v_cvt_pk_bf16_f32 v131, v131, s0
	ds_write_b16 v228, v131 offset:4352
	v_add_f32_e32 v131, v121, v129
	v_cvt_pk_bf16_f32 v131, v131, s0
	ds_write_b16 v228, v131 offset:4624
	v_add_f32_e32 v131, v122, v129
	v_cvt_pk_bf16_f32 v131, v131, s0
	ds_write_b16 v228, v131 offset:4896
	v_add_f32_e32 v131, v123, v129
	v_cvt_pk_bf16_f32 v131, v131, s0
	ds_write_b16 v228, v131 offset:5168
	v_add_f32_e32 v131, v124, v129
	v_cvt_pk_bf16_f32 v131, v131, s0
	ds_write_b16 v228, v131 offset:6528
	v_add_f32_e32 v131, v125, v129
	v_cvt_pk_bf16_f32 v131, v131, s0
	ds_write_b16 v228, v131 offset:6800
	v_add_f32_e32 v131, v126, v129
	v_add_f32_e32 v129, v127, v129
	v_cvt_pk_bf16_f32 v129, v129, s0
	ds_write_b16 v228, v129 offset:7344
	v_cvt_pk_bf16_f32 v131, v131, s0
	ds_write_b16 v228, v131 offset:7072
	v_mov_b32_e32 v130, v141
	v_add_f32_e32 v129, v96, v130
	v_cvt_pk_bf16_f32 v129, v129, s0
	ds_write_b16 v228, v129 offset:64
	v_add_f32_e32 v129, v97, v130
	v_cvt_pk_bf16_f32 v129, v129, s0
	ds_write_b16 v228, v129 offset:336
	v_add_f32_e32 v129, v98, v130
	v_cvt_pk_bf16_f32 v129, v129, s0
	ds_write_b16 v228, v129 offset:608
	v_add_f32_e32 v129, v99, v130
	v_cvt_pk_bf16_f32 v129, v129, s0
	ds_write_b16 v228, v129 offset:880
	v_add_f32_e32 v129, v100, v130
	v_cvt_pk_bf16_f32 v129, v129, s0
	ds_write_b16 v228, v129 offset:2240
	v_add_f32_e32 v129, v101, v130
	v_cvt_pk_bf16_f32 v129, v129, s0
	ds_write_b16 v228, v129 offset:2512
	v_add_f32_e32 v129, v102, v130
	v_cvt_pk_bf16_f32 v129, v129, s0
	ds_write_b16 v228, v129 offset:2784
	v_add_f32_e32 v129, v103, v130
	v_cvt_pk_bf16_f32 v129, v129, s0
	ds_write_b16 v228, v129 offset:3056
	v_add_f32_e32 v129, v104, v130
	v_cvt_pk_bf16_f32 v129, v129, s0
	ds_write_b16 v228, v129 offset:4416
	v_add_f32_e32 v129, v105, v130
	v_cvt_pk_bf16_f32 v129, v129, s0
	ds_write_b16 v228, v129 offset:4688
	v_add_f32_e32 v129, v106, v130
	v_cvt_pk_bf16_f32 v129, v129, s0
	ds_write_b16 v228, v129 offset:4960
	v_add_f32_e32 v129, v107, v130
	v_cvt_pk_bf16_f32 v129, v129, s0
	ds_write_b16 v228, v129 offset:5232
	v_add_f32_e32 v129, v108, v130
	v_cvt_pk_bf16_f32 v129, v129, s0
	ds_write_b16 v228, v129 offset:6592
	v_add_f32_e32 v129, v109, v130
	v_cvt_pk_bf16_f32 v129, v129, s0
	ds_write_b16 v228, v129 offset:6864
	v_add_f32_e32 v129, v110, v130
	v_cvt_pk_bf16_f32 v129, v129, s0
	ds_write_b16 v228, v129 offset:7136
	v_add_f32_e32 v129, v111, v130
	v_cvt_pk_bf16_f32 v129, v129, s0
	ds_write_b16 v228, v129 offset:7408
	v_mov_b32_e32 v129, v140
	v_add_f32_e32 v131, v80, v129
	v_cvt_pk_bf16_f32 v131, v131, s0
	ds_write_b16 v228, v131 offset:8704
	v_add_f32_e32 v131, v81, v129
	v_cvt_pk_bf16_f32 v131, v131, s0
	ds_write_b16 v228, v131 offset:8976
	v_add_f32_e32 v131, v82, v129
	v_cvt_pk_bf16_f32 v131, v131, s0
	ds_write_b16 v228, v131 offset:9248
	v_add_f32_e32 v131, v83, v129
	v_cvt_pk_bf16_f32 v131, v131, s0
	ds_write_b16 v228, v131 offset:9520
	v_add_f32_e32 v131, v84, v129
	v_cvt_pk_bf16_f32 v131, v131, s0
	ds_write_b16 v228, v131 offset:10880
	v_add_f32_e32 v131, v85, v129
	v_cvt_pk_bf16_f32 v131, v131, s0
	ds_write_b16 v228, v131 offset:11152
	v_add_f32_e32 v131, v86, v129
	v_cvt_pk_bf16_f32 v131, v131, s0
	ds_write_b16 v228, v131 offset:11424
	v_add_f32_e32 v131, v87, v129
	v_cvt_pk_bf16_f32 v131, v131, s0
	ds_write_b16 v228, v131 offset:11696
	v_add_f32_e32 v131, v88, v129
	v_cvt_pk_bf16_f32 v131, v131, s0
	ds_write_b16 v228, v131 offset:13056
	v_add_f32_e32 v131, v89, v129
	v_cvt_pk_bf16_f32 v131, v131, s0
	ds_write_b16 v228, v131 offset:13328
	v_add_f32_e32 v131, v90, v129
	v_cvt_pk_bf16_f32 v131, v131, s0
	ds_write_b16 v228, v131 offset:13600
	v_add_f32_e32 v131, v91, v129
	v_cvt_pk_bf16_f32 v131, v131, s0
	ds_write_b16 v228, v131 offset:13872
	v_add_f32_e32 v131, v92, v129
	v_cvt_pk_bf16_f32 v131, v131, s0
	ds_write_b16 v228, v131 offset:15232
	v_add_f32_e32 v131, v93, v129
	v_cvt_pk_bf16_f32 v131, v131, s0
	ds_write_b16 v228, v131 offset:15504
	v_add_f32_e32 v131, v94, v129
	v_add_f32_e32 v129, v95, v129
	v_cvt_pk_bf16_f32 v131, v131, s0
	v_cvt_pk_bf16_f32 v129, v129, s0
	ds_write_b16 v228, v131 offset:15776
	ds_write_b16 v228, v129 offset:16048
	v_mov_b32_e32 v130, v141
	v_add_f32_e32 v129, v64, v130
	v_cvt_pk_bf16_f32 v129, v129, s0
	ds_write_b16 v228, v129 offset:8768
	v_add_f32_e32 v129, v65, v130
	v_cvt_pk_bf16_f32 v129, v129, s0
	ds_write_b16 v228, v129 offset:9040
	v_add_f32_e32 v129, v66, v130
	v_cvt_pk_bf16_f32 v129, v129, s0
	ds_write_b16 v228, v129 offset:9312
	v_add_f32_e32 v129, v67, v130
; DEV unsigned short f2bf(float f) { return (unsigned short)(pack2(f, 0.f) & 0xFFFFu); }
; template <int EPI>
; __device__ void gemm_phase256(const Params& P, int l, const bf16_t* __restrict__ A, const bf16_t* __restrict__ Bt, int NT, char* smem) {
;     ...
; #pragma unroll
;       for (int mi = 0; mi < 4; ++mi)
; #pragma unroll
;         for (int ni = 0; ni < 2; ++ni) {
;           const int col = wn * 64 + ni * 32 + lr;
;           const int n = n0 + col;
;           const float bias = (EPI == 0) ? ((n < NIN) ? P.b_in[l * NIN + n] : 0.f) : 0.f;
;           const int rb = wm * 128 + mi * 32 + 4 * hk;
; #pragma unroll
;           for (int i = 0; i < 16; ++i) Cs[(rb + (i & 3) + 8 * (i >> 2)) * 136 + col] = f2bf(acc[mi][ni][i] + bias);
;         }
	v_cvt_pk_bf16_f32 v129, v129, s0
	ds_write_b16 v228, v129 offset:9584
	v_add_f32_e32 v129, v68, v130
	v_cvt_pk_bf16_f32 v129, v129, s0
	ds_write_b16 v228, v129 offset:10944
	v_add_f32_e32 v129, v69, v130
	v_cvt_pk_bf16_f32 v129, v129, s0
	ds_write_b16 v228, v129 offset:11216
	v_add_f32_e32 v129, v70, v130
	v_cvt_pk_bf16_f32 v129, v129, s0
	ds_write_b16 v228, v129 offset:11488
	v_add_f32_e32 v129, v71, v130
	v_cvt_pk_bf16_f32 v129, v129, s0
	ds_write_b16 v228, v129 offset:11760
	v_add_f32_e32 v129, v72, v130
	v_cvt_pk_bf16_f32 v129, v129, s0
	ds_write_b16 v228, v129 offset:13120
	v_add_f32_e32 v129, v73, v130
	v_cvt_pk_bf16_f32 v129, v129, s0
	ds_write_b16 v228, v129 offset:13392
	v_add_f32_e32 v129, v74, v130
	v_cvt_pk_bf16_f32 v129, v129, s0
	ds_write_b16 v228, v129 offset:13664
	v_add_f32_e32 v129, v75, v130
	v_cvt_pk_bf16_f32 v129, v129, s0
	ds_write_b16 v228, v129 offset:13936
	v_add_f32_e32 v129, v76, v130
	v_cvt_pk_bf16_f32 v129, v129, s0
	ds_write_b16 v228, v129 offset:15296
	v_add_f32_e32 v129, v77, v130
	v_cvt_pk_bf16_f32 v129, v129, s0
	ds_write_b16 v228, v129 offset:15568
	v_add_f32_e32 v129, v78, v130
	v_cvt_pk_bf16_f32 v129, v129, s0
	ds_write_b16 v228, v129 offset:15840
	v_add_f32_e32 v129, v79, v130
	v_cvt_pk_bf16_f32 v129, v129, s0
	ds_write_b16 v228, v129 offset:16112
	v_mov_b32_e32 v129, v140
	v_add_f32_e32 v131, v48, v129
	v_cvt_pk_bf16_f32 v131, v131, s0
	ds_write_b16 v228, v131 offset:17408
	v_add_f32_e32 v131, v49, v129
	v_cvt_pk_bf16_f32 v131, v131, s0
	ds_write_b16 v228, v131 offset:17680
	v_add_f32_e32 v131, v50, v129
	v_cvt_pk_bf16_f32 v131, v131, s0
	ds_write_b16 v228, v131 offset:17952
	v_add_f32_e32 v131, v51, v129
	v_cvt_pk_bf16_f32 v131, v131, s0
	ds_write_b16 v228, v131 offset:18224
	v_add_f32_e32 v131, v52, v129
	v_cvt_pk_bf16_f32 v131, v131, s0
	ds_write_b16 v228, v131 offset:19584
	v_add_f32_e32 v131, v53, v129
	v_cvt_pk_bf16_f32 v131, v131, s0
	ds_write_b16 v228, v131 offset:19856
	v_add_f32_e32 v131, v54, v129
	v_cvt_pk_bf16_f32 v131, v131, s0
	ds_write_b16 v228, v131 offset:20128
	v_add_f32_e32 v131, v55, v129
	v_cvt_pk_bf16_f32 v131, v131, s0
	ds_write_b16 v228, v131 offset:20400
	v_add_f32_e32 v131, v56, v129
	v_cvt_pk_bf16_f32 v131, v131, s0
	ds_write_b16 v228, v131 offset:21760
	v_add_f32_e32 v131, v57, v129
	v_cvt_pk_bf16_f32 v131, v131, s0
	ds_write_b16 v228, v131 offset:22032
	v_add_f32_e32 v131, v58, v129
	v_cvt_pk_bf16_f32 v131, v131, s0
	ds_write_b16 v228, v131 offset:22304
	v_add_f32_e32 v131, v59, v129
	v_cvt_pk_bf16_f32 v131, v131, s0
	ds_write_b16 v228, v131 offset:22576
	v_add_f32_e32 v131, v60, v129
	v_cvt_pk_bf16_f32 v131, v131, s0
	ds_write_b16 v228, v131 offset:23936
	v_add_f32_e32 v131, v61, v129
	v_cvt_pk_bf16_f32 v131, v131, s0
	ds_write_b16 v228, v131 offset:24208
	v_add_f32_e32 v131, v62, v129
	v_add_f32_e32 v129, v63, v129
	v_cvt_pk_bf16_f32 v131, v131, s0
	v_cvt_pk_bf16_f32 v129, v129, s0
	ds_write_b16 v228, v131 offset:24480
	ds_write_b16 v228, v129 offset:24752
	v_mov_b32_e32 v130, v141
	v_add_f32_e32 v129, v32, v130
	v_cvt_pk_bf16_f32 v129, v129, s0
	ds_write_b16 v228, v129 offset:17472
	v_add_f32_e32 v129, v33, v130
	v_cvt_pk_bf16_f32 v129, v129, s0
	ds_write_b16 v228, v129 offset:17744
	v_add_f32_e32 v129, v34, v130
	v_cvt_pk_bf16_f32 v129, v129, s0
	ds_write_b16 v228, v129 offset:18016
	v_add_f32_e32 v129, v35, v130
	v_cvt_pk_bf16_f32 v129, v129, s0
	ds_write_b16 v228, v129 offset:18288
	v_add_f32_e32 v129, v36, v130
	v_cvt_pk_bf16_f32 v129, v129, s0
	ds_write_b16 v228, v129 offset:19648
	v_add_f32_e32 v129, v37, v130
	v_cvt_pk_bf16_f32 v129, v129, s0
	ds_write_b16 v228, v129 offset:19920
	v_add_f32_e32 v129, v38, v130
	v_cvt_pk_bf16_f32 v129, v129, s0
	ds_write_b16 v228, v129 offset:20192
	v_add_f32_e32 v129, v39, v130
	v_cvt_pk_bf16_f32 v129, v129, s0
	ds_write_b16 v228, v129 offset:20464
	v_add_f32_e32 v129, v40, v130
	v_cvt_pk_bf16_f32 v129, v129, s0
	ds_write_b16 v228, v129 offset:21824
	v_add_f32_e32 v129, v41, v130
	v_cvt_pk_bf16_f32 v129, v129, s0
	ds_write_b16 v228, v129 offset:22096
	v_add_f32_e32 v129, v42, v130
	v_cvt_pk_bf16_f32 v129, v129, s0
	ds_write_b16 v228, v129 offset:22368
; DEV unsigned short f2bf(float f) { return (unsigned short)(pack2(f, 0.f) & 0xFFFFu); }
; template <int EPI>
; __device__ void gemm_phase256(const Params& P, int l, const bf16_t* __restrict__ A, const bf16_t* __restrict__ Bt, int NT, char* smem) {
;     ...
; #pragma unroll
;       for (int mi = 0; mi < 4; ++mi)
; #pragma unroll
;         for (int ni = 0; ni < 2; ++ni) {
;           const int col = wn * 64 + ni * 32 + lr;
;           const int n = n0 + col;
;           const float bias = (EPI == 0) ? ((n < NIN) ? P.b_in[l * NIN + n] : 0.f) : 0.f;
;           const int rb = wm * 128 + mi * 32 + 4 * hk;
; #pragma unroll
;           for (int i = 0; i < 16; ++i) Cs[(rb + (i & 3) + 8 * (i >> 2)) * 136 + col] = f2bf(acc[mi][ni][i] + bias);
;         }
;       __syncthreads();
;       bf16_t* dstb; int dstride, cbase, nvalid;
;       if (EPI == 0) { dstb = P.H; dstride = HS; cbase = n0 - (nt == 16 ? 128 : (nt == 18 ? 256 : 0)); nvalid = (NIN - n0 < 128) ? (NIN - n0) : 128; }
	v_add_f32_e32 v129, v43, v130
	v_cvt_pk_bf16_f32 v129, v129, s0
	ds_write_b16 v228, v129 offset:22640
	v_add_f32_e32 v129, v44, v130
	v_cvt_pk_bf16_f32 v129, v129, s0
	ds_write_b16 v228, v129 offset:24000
	v_add_f32_e32 v129, v45, v130
	v_cvt_pk_bf16_f32 v129, v129, s0
	ds_write_b16 v228, v129 offset:24272
	v_add_f32_e32 v129, v46, v130
	v_cvt_pk_bf16_f32 v129, v129, s0
	ds_write_b16 v228, v129 offset:24544
	v_add_f32_e32 v129, v47, v130
	v_cvt_pk_bf16_f32 v129, v129, s0
	ds_write_b16 v228, v129 offset:24816
	v_mov_b32_e32 v129, v140
	v_add_f32_e32 v128, v16, v129
	v_cvt_pk_bf16_f32 v128, v128, s0
	ds_write_b16 v228, v128 offset:26112
	v_add_f32_e32 v128, v17, v129
	v_cvt_pk_bf16_f32 v128, v128, s0
	ds_write_b16 v228, v128 offset:26384
	v_add_f32_e32 v128, v18, v129
	v_cvt_pk_bf16_f32 v128, v128, s0
	ds_write_b16 v228, v128 offset:26656
	v_add_f32_e32 v128, v19, v129
	v_cvt_pk_bf16_f32 v128, v128, s0
	ds_write_b16 v228, v128 offset:26928
	v_add_f32_e32 v128, v20, v129
	v_cvt_pk_bf16_f32 v128, v128, s0
	ds_write_b16 v228, v128 offset:28288
	v_add_f32_e32 v128, v21, v129
	v_cvt_pk_bf16_f32 v128, v128, s0
	ds_write_b16 v228, v128 offset:28560
	v_add_f32_e32 v128, v22, v129
	v_cvt_pk_bf16_f32 v128, v128, s0
	ds_write_b16 v228, v128 offset:28832
	v_add_f32_e32 v128, v23, v129
	v_cvt_pk_bf16_f32 v128, v128, s0
	ds_write_b16 v228, v128 offset:29104
	v_add_f32_e32 v128, v24, v129
	v_cvt_pk_bf16_f32 v128, v128, s0
	ds_write_b16 v228, v128 offset:30464
	v_add_f32_e32 v128, v25, v129
	v_cvt_pk_bf16_f32 v128, v128, s0
	ds_write_b16 v228, v128 offset:30736
	v_add_f32_e32 v128, v26, v129
	v_cvt_pk_bf16_f32 v128, v128, s0
	ds_write_b16 v228, v128 offset:31008
	v_add_f32_e32 v128, v27, v129
	v_cvt_pk_bf16_f32 v128, v128, s0
	ds_write_b16 v228, v128 offset:31280
	v_add_f32_e32 v128, v28, v129
	v_cvt_pk_bf16_f32 v128, v128, s0
	ds_write_b16 v228, v128 offset:32640
	v_add_f32_e32 v128, v29, v129
	v_cvt_pk_bf16_f32 v128, v128, s0
	ds_write_b16 v228, v128 offset:32912
	v_add_f32_e32 v128, v30, v129
	v_cvt_pk_bf16_f32 v128, v128, s0
	ds_write_b16 v228, v128 offset:33184
	v_add_f32_e32 v128, v31, v129
	v_cvt_pk_bf16_f32 v128, v128, s0
	ds_write_b16 v228, v128 offset:33456
	v_mov_b32_e32 v130, v141
	v_add_f32_e32 v128, v0, v130
	v_cvt_pk_bf16_f32 v128, v128, s0
	ds_write_b16 v228, v128 offset:26176
	v_add_f32_e32 v128, v1, v130
	v_cvt_pk_bf16_f32 v128, v128, s0
	ds_write_b16 v228, v128 offset:26448
	v_add_f32_e32 v128, v2, v130
	v_cvt_pk_bf16_f32 v128, v128, s0
	ds_write_b16 v228, v128 offset:26720
	v_add_f32_e32 v128, v3, v130
	v_cvt_pk_bf16_f32 v128, v128, s0
	ds_write_b16 v228, v128 offset:26992
	v_add_f32_e32 v128, v4, v130
	v_cvt_pk_bf16_f32 v128, v128, s0
	ds_write_b16 v228, v128 offset:28352
	v_add_f32_e32 v128, v5, v130
	v_cvt_pk_bf16_f32 v128, v128, s0
	ds_write_b16 v228, v128 offset:28624
	v_add_f32_e32 v128, v6, v130
	v_cvt_pk_bf16_f32 v128, v128, s0
	ds_write_b16 v228, v128 offset:28896
	v_add_f32_e32 v128, v7, v130
	v_cvt_pk_bf16_f32 v128, v128, s0
	ds_write_b16 v228, v128 offset:29168
	v_add_f32_e32 v128, v8, v130
	v_cvt_pk_bf16_f32 v128, v128, s0
	ds_write_b16 v228, v128 offset:30528
	v_add_f32_e32 v128, v9, v130
	v_cvt_pk_bf16_f32 v128, v128, s0
	ds_write_b16 v228, v128 offset:30800
	v_add_f32_e32 v128, v10, v130
	v_cvt_pk_bf16_f32 v128, v128, s0
	ds_write_b16 v228, v128 offset:31072
	v_add_f32_e32 v128, v11, v130
	v_cvt_pk_bf16_f32 v128, v128, s0
	ds_write_b16 v228, v128 offset:31344
	v_add_f32_e32 v128, v12, v130
	v_cvt_pk_bf16_f32 v128, v128, s0
	ds_write_b16 v228, v128 offset:32704
	v_add_f32_e32 v128, v13, v130
	v_cvt_pk_bf16_f32 v128, v128, s0
	s_cmp_eq_u32 s33, 18
	ds_write_b16 v228, v128 offset:32976
	v_add_f32_e32 v128, v14, v130
	s_cselect_b32 s37, 0xffffff00, 0
	s_cmp_lg_u32 s33, 16
	v_cvt_pk_bf16_f32 v128, v128, s0
	s_cselect_b32 s37, s37, 0xffffff80
	ds_write_b16 v228, v128 offset:33248
	v_add_f32_e32 v128, v15, v130
	s_add_i32 s38, s37, s0
	v_cvt_pk_bf16_f32 v128, v128, s0
	s_ashr_i32 s39, s38, 31
	ds_write_b16 v228, v128 offset:33520
	s_mov_b32 s1, 0
	v_cmp_lt_i32_e32 vcc, s0, v185
	v_lshl_add_u64 v[128:129], s[38:39], 1, v[192:193]
	s_waitcnt lgkmcnt(0)
	s_barrier
	s_branch .LBB0_265
